# MLA attention: row-max exchange by v_permlane32_swap and the LDS wait moved down to the first PV MFMA that consumes the V fragments
# baseline (speedup 1.0000x reference)
; DI float fexp2(float x) { return __builtin_amdgcn_exp2f(x); }
;     ...
;             float mt = fmaxf(s[j][0], s[j][1]);
; #pragma unroll
;             for (int i = 2; i < 16; ++i) mt = fmaxf(mt, s[j][i]);
;             mt = fmaxf(mt, __shfl_xor(mt, 32));
;             if (MODE == 1) mt *= c2;
;             const float cand = fmaxf(mrun, mt);
;             if (__any(cand > mrun + 8.f)) {
;               const float alpha = fexp2(mrun - cand);
;               mrun = cand; lsum *= alpha;
; #pragma unroll
;               for (int i = 0; i < 16; ++i) { oacc[0][i] *= alpha; oacc[1][i] *= alpha; }
;             }
;             const float nm = -mrun;
; #pragma unroll
;             for (int i = 0; i < 16; ++i) {
;               const float p = (MODE == 1) ? fexp2(fmaf(s[j][i], c2, nm)) : fexp2(s[j][i] + nm);
;               lsum += p; s[j][i] = p;
;             }
;             pvm(j);
.LBB0_830:
	s_or_b64 exec, exec, s[8:9]
	v_add_f32_e32 v128, v201, v209
	v_add_f32_e32 v128, v211, v128
	v_max_f32_e32 v129, v33, v33
	v_max_f32_e32 v130, v32, v32
	v_add_f32_e32 v128, v212, v128
	v_max_f32_e32 v129, v130, v129
	v_add_f32_e32 v128, v213, v128
	v_max3_f32 v129, v129, v34, v35
	v_add_f32_e32 v128, v214, v128
	v_max3_f32 v129, v129, v36, v37
	v_add_f32_e32 v128, v215, v128
	v_max3_f32 v129, v129, v38, v39
	v_add_f32_e32 v128, v216, v128
	v_max3_f32 v129, v129, v40, v41
	v_add_f32_e32 v128, v217, v128
	v_max3_f32 v129, v129, v42, v43
	v_add_f32_e32 v128, v218, v128
	v_max3_f32 v129, v129, v44, v45
	v_add_f32_e32 v128, v219, v128
	v_max3_f32 v130, v129, v46, v47
	v_add_f32_e32 v128, v220, v128
	v_mov_b32_e32 v131, v130
	v_mov_b32_e32 v230, v130
	s_nop 1
	v_permlane32_swap_b32_e32 v131, v230
	v_max_f32_e32 v131, v131, v230
	v_add_f32_e32 v128, v221, v128
	v_add_f32_e32 v128, v203, v128
	v_add_f32_e32 v128, v207, v128
	v_add_f32_e32 v128, v208, v128
	v_add_f32_e32 v129, v210, v128
	v_max_f32_e32 v128, v131, v131
	v_max_f32_e32 v128, v130, v128
	v_mul_f32_e32 v128, 0x3e16c73f, v128
	v_max_f32_e32 v130, v202, v202
	v_max_f32_e32 v130, v130, v128
	v_add_f32_e32 v128, 0x41000000, v202
	v_cmp_gt_f32_e32 vcc, v130, v128
	s_cbranch_vccz .LBB0_853
	v_sub_f32_e32 v128, v202, v130
	v_exp_f32_e32 v128, v128
	v_mov_b32_e32 v202, v130
	v_mul_f32_e32 v129, v129, v128
	v_pk_mul_f32 v[30:31], v[30:31], v[128:129] op_sel_hi:[1,0]
	v_pk_mul_f32 v[28:29], v[28:29], v[128:129] op_sel_hi:[1,0]
	v_pk_mul_f32 v[26:27], v[26:27], v[128:129] op_sel_hi:[1,0]
	v_pk_mul_f32 v[24:25], v[24:25], v[128:129] op_sel_hi:[1,0]
	v_pk_mul_f32 v[22:23], v[22:23], v[128:129] op_sel_hi:[1,0]
	v_pk_mul_f32 v[20:21], v[20:21], v[128:129] op_sel_hi:[1,0]
	v_pk_mul_f32 v[18:19], v[18:19], v[128:129] op_sel_hi:[1,0]
	v_pk_mul_f32 v[16:17], v[16:17], v[128:129] op_sel_hi:[1,0]
	v_pk_mul_f32 v[14:15], v[14:15], v[128:129] op_sel_hi:[1,0]
	v_pk_mul_f32 v[12:13], v[12:13], v[128:129] op_sel_hi:[1,0]
	v_pk_mul_f32 v[10:11], v[10:11], v[128:129] op_sel_hi:[1,0]
	v_pk_mul_f32 v[8:9], v[8:9], v[128:129] op_sel_hi:[1,0]
	v_pk_mul_f32 v[6:7], v[6:7], v[128:129] op_sel_hi:[1,0]
	v_pk_mul_f32 v[4:5], v[4:5], v[128:129] op_sel_hi:[1,0]
	v_pk_mul_f32 v[2:3], v[2:3], v[128:129] op_sel_hi:[1,0]
	v_pk_mul_f32 v[0:1], v[0:1], v[128:129] op_sel_hi:[1,0]
	v_xor_b32_e32 v128, 0x80000000, v130
.LBB0_832:
	v_fmamk_f32 v32, v32, 0x3e16c73f, v128
	v_exp_f32_e32 v32, v32
	v_fmamk_f32 v33, v33, 0x3e16c73f, v128
	v_exp_f32_e32 v33, v33
	v_fmamk_f32 v34, v34, 0x3e16c73f, v128
	v_exp_f32_e32 v34, v34
	v_fmamk_f32 v35, v35, 0x3e16c73f, v128
	v_fmamk_f32 v36, v36, 0x3e16c73f, v128
	v_fmamk_f32 v37, v37, 0x3e16c73f, v128
	v_fmamk_f32 v38, v38, 0x3e16c73f, v128
	v_fmamk_f32 v39, v39, 0x3e16c73f, v128
	v_exp_f32_e32 v35, v35
	v_exp_f32_e32 v36, v36
	v_exp_f32_e32 v37, v37
	v_exp_f32_e32 v38, v38
	v_exp_f32_e32 v39, v39
	v_add_f32_e32 v129, v32, v129
	v_add_f32_e32 v129, v33, v129
	v_add_f32_e32 v129, v34, v129
	v_add_f32_e32 v129, v35, v129
	v_cvt_pk_bf16_f32 v32, v32, v33
	v_cvt_pk_bf16_f32 v33, v34, v35
	v_cvt_pk_bf16_f32 v34, v36, v37
	v_cvt_pk_bf16_f32 v35, v38, v39
	v_fmamk_f32 v40, v40, 0x3e16c73f, v128
	v_fmamk_f32 v41, v41, 0x3e16c73f, v128
	s_waitcnt lgkmcnt(0)
	v_mfma_f32_32x32x16_bf16 v[16:31], v[60:63], v[32:35], v[16:31]
	v_fmamk_f32 v42, v42, 0x3e16c73f, v128
	v_fmamk_f32 v43, v43, 0x3e16c73f, v128
	v_fmamk_f32 v44, v44, 0x3e16c73f, v128
	v_fmamk_f32 v45, v45, 0x3e16c73f, v128
	v_fmamk_f32 v46, v46, 0x3e16c73f, v128
	v_fmac_f32_e32 v128, 0x3e16c73f, v47
	v_exp_f32_e32 v40, v40
	v_mfma_f32_32x32x16_bf16 v[0:15], v[56:59], v[32:35], v[0:15]
	v_exp_f32_e32 v41, v41
	v_exp_f32_e32 v42, v42
	v_exp_f32_e32 v43, v43
	v_exp_f32_e32 v44, v44
	v_exp_f32_e32 v45, v45
	v_exp_f32_e32 v46, v46
	v_exp_f32_e32 v47, v128
	v_add_f32_e32 v129, v36, v129
	v_add_f32_e32 v129, v37, v129
	v_add_f32_e32 v129, v38, v129
	v_add_f32_e32 v129, v39, v129
	v_cvt_pk_bf16_f32 v32, v40, v41
	v_cvt_pk_bf16_f32 v33, v42, v43
	v_cvt_pk_bf16_f32 v34, v44, v45
	v_cvt_pk_bf16_f32 v35, v46, v47
	v_add_f32_e32 v129, v40, v129
	v_add_f32_e32 v129, v41, v129
	v_mfma_f32_32x32x16_bf16 v[16:31], v[52:55], v[32:35], v[16:31]
	v_add_f32_e32 v129, v42, v129
	v_add_f32_e32 v129, v43, v129
	v_add_f32_e32 v129, v44, v129
	v_add_f32_e32 v129, v45, v129
	v_add_f32_e32 v129, v46, v129
	v_add_f32_e32 v201, v47, v129
	v_mov_b32_e32 v203, v202
	v_mfma_f32_32x32x16_bf16 v[0:15], v[48:51], v[32:35], v[0:15]

; DI float fexp2(float x) { return __builtin_amdgcn_exp2f(x); }
;     ...
;             float mt = fmaxf(s[j][0], s[j][1]);
; #pragma unroll
;             for (int i = 2; i < 16; ++i) mt = fmaxf(mt, s[j][i]);
;             mt = fmaxf(mt, __shfl_xor(mt, 32));
;             if (MODE == 1) mt *= c2;
;             const float cand = fmaxf(mrun, mt);
;             if (__any(cand > mrun + 8.f)) {
;               const float alpha = fexp2(mrun - cand);
;               mrun = cand; lsum *= alpha;
; #pragma unroll
;               for (int i = 0; i < 16; ++i) { oacc[0][i] *= alpha; oacc[1][i] *= alpha; }
;             }
;             const float nm = -mrun;
; #pragma unroll
.LBB0_837:
	s_or_b64 exec, exec, s[8:9]
	v_max_f32_e32 v202, v49, v49
	v_max_f32_e32 v205, v48, v48
	v_max_f32_e32 v202, v205, v202
	v_max3_f32 v202, v202, v50, v51
	v_max3_f32 v202, v202, v52, v53
	v_max3_f32 v202, v202, v54, v55
	v_and_b32_e32 v208, 64, v182
	v_max3_f32 v202, v202, v56, v57
	v_xor_b32_e32 v205, 32, v182
	v_add_u32_e32 v208, 64, v208
	v_max3_f32 v202, v202, v58, v59
	v_cmp_lt_i32_e32 vcc, v205, v208
	v_max3_f32 v202, v202, v60, v61
	v_max3_f32 v202, v202, v62, v63
	v_cndmask_b32_e32 v205, v182, v205, vcc
	v_lshlrev_b32_e32 v205, 2, v205
	v_mov_b32_e32 v208, v202
	v_mov_b32_e32 v230, v202
	s_nop 1
	v_permlane32_swap_b32_e32 v208, v230
	v_max_f32_e32 v208, v208, v230
	v_max_f32_e32 v208, v208, v208
	v_max_f32_e32 v202, v202, v208
	v_mul_f32_e32 v202, 0x3e16c73f, v202
	v_max_f32_e32 v208, v203, v203
	v_max_f32_e32 v202, v208, v202
	v_add_f32_e32 v208, 0x41000000, v203
	v_cmp_gt_f32_e32 vcc, v202, v208
	s_cbranch_vccz .LBB0_839
	v_sub_f32_e32 v203, v203, v202
	v_exp_f32_e32 v208, v203
	s_nop 0
	v_mul_f32_e32 v201, v201, v208
	v_pk_mul_f32 v[30:31], v[30:31], v[208:209] op_sel_hi:[1,0]
	v_pk_mul_f32 v[28:29], v[28:29], v[208:209] op_sel_hi:[1,0]
	v_pk_mul_f32 v[26:27], v[26:27], v[208:209] op_sel_hi:[1,0]
	v_pk_mul_f32 v[24:25], v[24:25], v[208:209] op_sel_hi:[1,0]
	v_pk_mul_f32 v[22:23], v[22:23], v[208:209] op_sel_hi:[1,0]
	v_pk_mul_f32 v[20:21], v[20:21], v[208:209] op_sel_hi:[1,0]
	v_pk_mul_f32 v[18:19], v[18:19], v[208:209] op_sel_hi:[1,0]
	v_pk_mul_f32 v[16:17], v[16:17], v[208:209] op_sel_hi:[1,0]
	v_pk_mul_f32 v[14:15], v[14:15], v[208:209] op_sel_hi:[1,0]
	v_pk_mul_f32 v[12:13], v[12:13], v[208:209] op_sel_hi:[1,0]
	v_pk_mul_f32 v[10:11], v[10:11], v[208:209] op_sel_hi:[1,0]
	v_pk_mul_f32 v[8:9], v[8:9], v[208:209] op_sel_hi:[1,0]
	v_pk_mul_f32 v[6:7], v[6:7], v[208:209] op_sel_hi:[1,0]
	v_pk_mul_f32 v[4:5], v[4:5], v[208:209] op_sel_hi:[1,0]
	v_pk_mul_f32 v[2:3], v[2:3], v[208:209] op_sel_hi:[1,0]
	v_pk_mul_f32 v[0:1], v[0:1], v[208:209] op_sel_hi:[1,0]
	s_branch .LBB0_840

; DI float fexp2(float x) { return __builtin_amdgcn_exp2f(x); }
;     ...
;             ldv(j);
;             if (MODE == 2) {
; #pragma unroll
;               for (int g = 0; g < 4; ++g) {
;                 const f32x4 nf = *(const f32x4*)(Fl + buf * 64 + j * 32 + 8 * g + 4 * hh);
; #pragma unroll
;                 for (int e = 0; e < 4; ++e) s[j][4 * g + e] = fmaf(s[j][4 * g + e], c2, nf[e]);
;               }
;             }
;             if (diag) {
;               asm volatile("" ::: "memory");
; #pragma unroll
;               for (int i = 0; i < 16; ++i) s[j][i] = (j * 32 + 8 * (i >> 2) + (i & 3)) <= dq ? s[j][i] : -INFINITY;
;             }
;             float mt = fmaxf(s[j][0], s[j][1]);
; #pragma unroll
;             for (int i = 2; i < 16; ++i) mt = fmaxf(mt, s[j][i]);
;             mt = fmaxf(mt, __shfl_xor(mt, 32));
;             if (MODE == 1) mt *= c2;
;             const float cand = fmaxf(mrun, mt);
;             if (__any(cand > mrun + 8.f)) {
;               const float alpha = fexp2(mrun - cand);
;               mrun = cand; lsum *= alpha;
; #pragma unroll
;               for (int i = 0; i < 16; ++i) { oacc[0][i] *= alpha; oacc[1][i] *= alpha; }
;             }
;             const float nm = -mrun;
; #pragma unroll
;             for (int i = 0; i < 16; ++i) {
;               const float p = (MODE == 1) ? fexp2(fmaf(s[j][i], c2, nm)) : fexp2(s[j][i] + nm);
;               lsum += p; s[j][i] = p;
;             }
;             pvm(j);
.LBB0_840:
	v_fma_f32 v48, v48, s31, -v202
	v_exp_f32_e32 v210, v48
	v_fma_f32 v48, v49, s31, -v202
	v_exp_f32_e32 v212, v48
	v_fma_f32 v48, v50, s31, -v202
	v_exp_f32_e32 v213, v48
	v_fma_f32 v48, v51, s31, -v202
	v_exp_f32_e32 v214, v48
	v_fma_f32 v48, v52, s31, -v202
	v_exp_f32_e32 v215, v48
	v_fma_f32 v48, v53, s31, -v202
	v_exp_f32_e32 v216, v48
	v_fma_f32 v48, v54, s31, -v202
	v_exp_f32_e32 v217, v48
	v_fma_f32 v48, v55, s31, -v202
	v_exp_f32_e32 v218, v48
	v_fma_f32 v48, v56, s31, -v202
	v_exp_f32_e32 v219, v48
	v_fma_f32 v48, v57, s31, -v202
	v_exp_f32_e32 v220, v48
	v_fma_f32 v48, v58, s31, -v202
	v_exp_f32_e32 v221, v48
	v_fma_f32 v48, v59, s31, -v202
	v_exp_f32_e32 v222, v48
	v_fma_f32 v48, v60, s31, -v202
	v_exp_f32_e32 v203, v48
	v_fma_f32 v48, v61, s31, -v202
	v_exp_f32_e32 v208, v48
	v_fma_f32 v48, v62, s31, -v202
	v_exp_f32_e32 v209, v48
	v_fma_f32 v48, v63, s31, -v202
	v_exp_f32_e32 v211, v48
	v_cvt_pk_bf16_f32 v48, v210, v212
	v_cvt_pk_bf16_f32 v49, v213, v214
	v_cvt_pk_bf16_f32 v50, v215, v216
	v_cvt_pk_bf16_f32 v51, v217, v218
	s_nop 1
	s_waitcnt lgkmcnt(0)
	v_mfma_f32_32x32x16_bf16 v[16:31], v[140:143], v[48:51], v[16:31]
	v_mfma_f32_32x32x16_bf16 v[0:15], v[136:139], v[48:51], v[0:15]
	v_cvt_pk_bf16_f32 v48, v219, v220
	v_cvt_pk_bf16_f32 v49, v221, v222
	v_cvt_pk_bf16_f32 v50, v203, v208
	v_cvt_pk_bf16_f32 v51, v209, v211
	s_nop 1
	v_mfma_f32_32x32x16_bf16 v[16:31], v[128:131], v[48:51], v[16:31]
	v_mfma_f32_32x32x16_bf16 v[0:15], v[132:135], v[48:51], v[0:15]
	ds_read2_b64 v[60:63], v206 offset0:8 offset1:10
	ds_read2_b64 v[52:55], v206 offset0:12 offset1:14
	ds_read2_b64 v[56:59], v207 offset0:40 offset1:42
	ds_read2_b64 v[48:51], v207 offset0:44 offset1:46
	s_and_saveexec_b64 s[8:9], s[46:47]
	s_cbranch_execz .LBB0_842
	v_cmp_lt_i32_e32 vcc, 31, v204
	s_nop 1
	v_cndmask_b32_e32 v32, v185, v32, vcc
	v_cmp_lt_i32_e32 vcc, 32, v204
	s_nop 1
	v_cndmask_b32_e32 v33, v185, v33, vcc
	v_cmp_lt_i32_e32 vcc, 33, v204
	s_nop 1
	v_cndmask_b32_e32 v34, v185, v34, vcc
	v_cmp_lt_i32_e32 vcc, 34, v204
	s_nop 1
	v_cndmask_b32_e32 v35, v185, v35, vcc
	v_cmp_lt_i32_e32 vcc, 39, v204
	s_nop 1
	v_cndmask_b32_e32 v36, v185, v36, vcc
	v_cmp_lt_i32_e32 vcc, 40, v204
	s_nop 1
	v_cndmask_b32_e32 v37, v185, v37, vcc
	v_cmp_lt_i32_e32 vcc, 41, v204
	s_nop 1
	v_cndmask_b32_e32 v38, v185, v38, vcc
	v_cmp_lt_i32_e32 vcc, 42, v204
	s_nop 1
	v_cndmask_b32_e32 v39, v185, v39, vcc
	v_cmp_lt_i32_e32 vcc, 47, v204
	s_nop 1
	v_cndmask_b32_e32 v40, v185, v40, vcc
	v_cmp_lt_i32_e32 vcc, 48, v204
	s_nop 1
	v_cndmask_b32_e32 v41, v185, v41, vcc
	v_cmp_lt_i32_e32 vcc, 49, v204
	s_nop 1
	v_cndmask_b32_e32 v42, v185, v42, vcc
	v_cmp_lt_i32_e32 vcc, 50, v204
	s_nop 1
	v_cndmask_b32_e32 v43, v185, v43, vcc
	v_cmp_lt_i32_e32 vcc, 55, v204
	s_nop 1
	v_cndmask_b32_e32 v44, v185, v44, vcc
	v_cmp_lt_i32_e32 vcc, 56, v204
	s_nop 1
	v_cndmask_b32_e32 v45, v185, v45, vcc
	v_cmp_lt_i32_e32 vcc, 57, v204
	s_nop 1
	v_cndmask_b32_e32 v46, v185, v46, vcc
	v_cmp_lt_i32_e32 vcc, 58, v204
	s_nop 1
	v_cndmask_b32_e32 v47, v185, v47, vcc
.LBB0_842:
	s_or_b64 exec, exec, s[8:9]
	v_add_f32_e32 v128, v201, v210
	v_add_f32_e32 v128, v212, v128
	v_max_f32_e32 v129, v33, v33
	v_max_f32_e32 v130, v32, v32
	v_add_f32_e32 v128, v213, v128
	v_max_f32_e32 v129, v130, v129
	v_add_f32_e32 v128, v214, v128
	v_max3_f32 v129, v129, v34, v35
	v_add_f32_e32 v128, v215, v128
	v_max3_f32 v129, v129, v36, v37
	v_add_f32_e32 v128, v216, v128
	v_max3_f32 v129, v129, v38, v39
	v_add_f32_e32 v128, v217, v128
	v_max3_f32 v129, v129, v40, v41
	v_add_f32_e32 v128, v218, v128
	v_max3_f32 v129, v129, v42, v43
	v_add_f32_e32 v128, v219, v128
	v_max3_f32 v129, v129, v44, v45
	v_add_f32_e32 v128, v220, v128
	v_max3_f32 v130, v129, v46, v47
	v_add_f32_e32 v128, v221, v128
	v_mov_b32_e32 v131, v130
	v_mov_b32_e32 v230, v130
	s_nop 1
	v_permlane32_swap_b32_e32 v131, v230
	v_max_f32_e32 v131, v131, v230
	v_add_f32_e32 v128, v222, v128
	v_add_f32_e32 v128, v203, v128
	v_add_f32_e32 v128, v208, v128
	v_add_f32_e32 v128, v209, v128
	v_add_f32_e32 v129, v211, v128
	v_max_f32_e32 v128, v131, v131
	v_max_f32_e32 v128, v130, v128
	v_mul_f32_e32 v128, 0x3e16c73f, v128
	v_max_f32_e32 v130, v202, v202
	v_max_f32_e32 v130, v130, v128
	v_add_f32_e32 v128, 0x41000000, v202
	v_cmp_gt_f32_e32 vcc, v130, v128
	s_cbranch_vccz .LBB0_844
	v_sub_f32_e32 v128, v202, v130
	v_exp_f32_e32 v128, v128
	v_mov_b32_e32 v202, v130
	v_mul_f32_e32 v129, v129, v128
	v_pk_mul_f32 v[30:31], v[30:31], v[128:129] op_sel_hi:[1,0]
	v_pk_mul_f32 v[28:29], v[28:29], v[128:129] op_sel_hi:[1,0]
	v_pk_mul_f32 v[26:27], v[26:27], v[128:129] op_sel_hi:[1,0]
	v_pk_mul_f32 v[24:25], v[24:25], v[128:129] op_sel_hi:[1,0]
	v_pk_mul_f32 v[22:23], v[22:23], v[128:129] op_sel_hi:[1,0]
	v_pk_mul_f32 v[20:21], v[20:21], v[128:129] op_sel_hi:[1,0]
	v_pk_mul_f32 v[18:19], v[18:19], v[128:129] op_sel_hi:[1,0]
	v_pk_mul_f32 v[16:17], v[16:17], v[128:129] op_sel_hi:[1,0]
	v_pk_mul_f32 v[14:15], v[14:15], v[128:129] op_sel_hi:[1,0]
	v_pk_mul_f32 v[12:13], v[12:13], v[128:129] op_sel_hi:[1,0]
	v_pk_mul_f32 v[10:11], v[10:11], v[128:129] op_sel_hi:[1,0]
	v_pk_mul_f32 v[8:9], v[8:9], v[128:129] op_sel_hi:[1,0]
	v_pk_mul_f32 v[6:7], v[6:7], v[128:129] op_sel_hi:[1,0]
	v_pk_mul_f32 v[4:5], v[4:5], v[128:129] op_sel_hi:[1,0]
	v_pk_mul_f32 v[2:3], v[2:3], v[128:129] op_sel_hi:[1,0]
	v_pk_mul_f32 v[0:1], v[0:1], v[128:129] op_sel_hi:[1,0]
	v_xor_b32_e32 v128, 0x80000000, v130
	s_branch .LBB0_845

; DI float fexp2(float x) { return __builtin_amdgcn_exp2f(x); }
;     ...
;             float mt = fmaxf(s[j][0], s[j][1]);
; #pragma unroll
;             for (int i = 2; i < 16; ++i) mt = fmaxf(mt, s[j][i]);
;             mt = fmaxf(mt, __shfl_xor(mt, 32));
;             if (MODE == 1) mt *= c2;
;             const float cand = fmaxf(mrun, mt);
;             if (__any(cand > mrun + 8.f)) {
;               const float alpha = fexp2(mrun - cand);
;               mrun = cand; lsum *= alpha;
; #pragma unroll
;               for (int i = 0; i < 16; ++i) { oacc[0][i] *= alpha; oacc[1][i] *= alpha; }
;             }
;             const float nm = -mrun;
; #pragma unroll
.LBB0_850:
	s_or_b64 exec, exec, s[8:9]
	v_max_f32_e32 v202, v49, v49
	v_max_f32_e32 v204, v48, v48
	v_max_f32_e32 v202, v204, v202
	v_max3_f32 v202, v202, v50, v51
	v_max3_f32 v202, v202, v52, v53
	v_max3_f32 v202, v202, v54, v55
	v_and_b32_e32 v207, 64, v182
	v_max3_f32 v202, v202, v56, v57
	v_xor_b32_e32 v204, 32, v182
	v_add_u32_e32 v207, 64, v207
	v_max3_f32 v202, v202, v58, v59
	v_cmp_lt_i32_e32 vcc, v204, v207
	v_max3_f32 v202, v202, v60, v61
	v_max3_f32 v202, v202, v62, v63
	v_cndmask_b32_e32 v204, v182, v204, vcc
	v_lshlrev_b32_e32 v204, 2, v204
	v_mov_b32_e32 v207, v202
	v_mov_b32_e32 v230, v202
	s_nop 1
	v_permlane32_swap_b32_e32 v207, v230
	v_max_f32_e32 v207, v207, v230
	v_max_f32_e32 v207, v207, v207
	v_max_f32_e32 v202, v202, v207
	v_mul_f32_e32 v202, 0x3e16c73f, v202
	v_max_f32_e32 v207, v203, v203
	v_max_f32_e32 v202, v207, v202
	v_add_f32_e32 v207, 0x41000000, v203
	v_cmp_gt_f32_e32 vcc, v202, v207
	s_cbranch_vccz .LBB0_854
	v_sub_f32_e32 v203, v203, v202
	v_exp_f32_e32 v208, v203
	s_nop 0
	v_mul_f32_e32 v201, v201, v208
	v_pk_mul_f32 v[30:31], v[30:31], v[208:209] op_sel_hi:[1,0]
	v_pk_mul_f32 v[28:29], v[28:29], v[208:209] op_sel_hi:[1,0]
	v_pk_mul_f32 v[26:27], v[26:27], v[208:209] op_sel_hi:[1,0]
	v_pk_mul_f32 v[24:25], v[24:25], v[208:209] op_sel_hi:[1,0]
	v_pk_mul_f32 v[22:23], v[22:23], v[208:209] op_sel_hi:[1,0]
	v_pk_mul_f32 v[20:21], v[20:21], v[208:209] op_sel_hi:[1,0]
	v_pk_mul_f32 v[18:19], v[18:19], v[208:209] op_sel_hi:[1,0]
	v_pk_mul_f32 v[16:17], v[16:17], v[208:209] op_sel_hi:[1,0]
	v_pk_mul_f32 v[14:15], v[14:15], v[208:209] op_sel_hi:[1,0]
	v_pk_mul_f32 v[12:13], v[12:13], v[208:209] op_sel_hi:[1,0]
	v_pk_mul_f32 v[10:11], v[10:11], v[208:209] op_sel_hi:[1,0]
	v_pk_mul_f32 v[8:9], v[8:9], v[208:209] op_sel_hi:[1,0]
	v_pk_mul_f32 v[6:7], v[6:7], v[208:209] op_sel_hi:[1,0]
	v_pk_mul_f32 v[4:5], v[4:5], v[208:209] op_sel_hi:[1,0]
	v_pk_mul_f32 v[2:3], v[2:3], v[208:209] op_sel_hi:[1,0]
	v_pk_mul_f32 v[0:1], v[0:1], v[208:209] op_sel_hi:[1,0]
	s_branch .LBB0_855

; DI float fexp2(float x) { return __builtin_amdgcn_exp2f(x); }
;     ...
;             ldv(j);
;             if (MODE == 2) {
; #pragma unroll
;               for (int g = 0; g < 4; ++g) {
;                 const f32x4 nf = *(const f32x4*)(Fl + buf * 64 + j * 32 + 8 * g + 4 * hh);
; #pragma unroll
;                 for (int e = 0; e < 4; ++e) s[j][4 * g + e] = fmaf(s[j][4 * g + e], c2, nf[e]);
;               }
;             }
;             if (diag) {
;               asm volatile("" ::: "memory");
; #pragma unroll
;               for (int i = 0; i < 16; ++i) s[j][i] = (j * 32 + 8 * (i >> 2) + (i & 3)) <= dq ? s[j][i] : -INFINITY;
;             }
;             float mt = fmaxf(s[j][0], s[j][1]);
; #pragma unroll
;             for (int i = 2; i < 16; ++i) mt = fmaxf(mt, s[j][i]);
;             mt = fmaxf(mt, __shfl_xor(mt, 32));
;             if (MODE == 1) mt *= c2;
;             const float cand = fmaxf(mrun, mt);
;             if (__any(cand > mrun + 8.f)) {
;               const float alpha = fexp2(mrun - cand);
;               mrun = cand; lsum *= alpha;
; #pragma unroll
;               for (int i = 0; i < 16; ++i) { oacc[0][i] *= alpha; oacc[1][i] *= alpha; }
;             }
;             const float nm = -mrun;
; #pragma unroll
;             for (int i = 0; i < 16; ++i) {
;               const float p = (MODE == 1) ? fexp2(fmaf(s[j][i], c2, nm)) : fexp2(s[j][i] + nm);
;               lsum += p; s[j][i] = p;
;             }
;             pvm(j);
.LBB0_855:
	v_fma_f32 v48, v48, s31, -v202
	v_exp_f32_e32 v209, v48
	v_fma_f32 v48, v49, s31, -v202
	v_exp_f32_e32 v211, v48
	v_fma_f32 v48, v50, s31, -v202
	v_exp_f32_e32 v212, v48
	v_fma_f32 v48, v51, s31, -v202
	v_exp_f32_e32 v213, v48
	v_fma_f32 v48, v52, s31, -v202
	v_exp_f32_e32 v214, v48
	v_fma_f32 v48, v53, s31, -v202
	v_exp_f32_e32 v215, v48
	v_fma_f32 v48, v54, s31, -v202
	v_exp_f32_e32 v216, v48
	v_fma_f32 v48, v55, s31, -v202
	v_exp_f32_e32 v217, v48
	v_fma_f32 v48, v56, s31, -v202
	v_exp_f32_e32 v218, v48
	v_fma_f32 v48, v57, s31, -v202
	v_exp_f32_e32 v219, v48
	v_fma_f32 v48, v58, s31, -v202
	v_exp_f32_e32 v220, v48
	v_fma_f32 v48, v59, s31, -v202
	v_exp_f32_e32 v221, v48
	v_fma_f32 v48, v60, s31, -v202
	v_exp_f32_e32 v203, v48
	v_fma_f32 v48, v61, s31, -v202
	v_exp_f32_e32 v207, v48
	v_fma_f32 v48, v62, s31, -v202
	v_exp_f32_e32 v208, v48
	v_fma_f32 v48, v63, s31, -v202
	v_exp_f32_e32 v210, v48
	v_cvt_pk_bf16_f32 v48, v209, v211
	v_cvt_pk_bf16_f32 v49, v212, v213
	v_cvt_pk_bf16_f32 v50, v214, v215
	v_cvt_pk_bf16_f32 v51, v216, v217
	s_nop 1
	s_waitcnt lgkmcnt(0)
	v_mfma_f32_32x32x16_bf16 v[16:31], v[140:143], v[48:51], v[16:31]
	v_mfma_f32_32x32x16_bf16 v[0:15], v[136:139], v[48:51], v[0:15]
	v_cvt_pk_bf16_f32 v48, v218, v219
	v_cvt_pk_bf16_f32 v49, v220, v221
	v_cvt_pk_bf16_f32 v50, v203, v207
	v_cvt_pk_bf16_f32 v51, v208, v210
	s_nop 1
	v_mfma_f32_32x32x16_bf16 v[16:31], v[128:131], v[48:51], v[16:31]
	v_mfma_f32_32x32x16_bf16 v[0:15], v[132:135], v[48:51], v[0:15]
	ds_read2_b64 v[60:63], v205 offset0:72 offset1:74
	ds_read2_b64 v[52:55], v205 offset0:76 offset1:78
	ds_read2_b64 v[56:59], v206 offset0:104 offset1:106
	ds_read2_b64 v[48:51], v206 offset0:108 offset1:110
	s_and_saveexec_b64 s[8:9], s[46:47]
	s_cbranch_execz .LBB0_830
	v_cmp_lt_i32_e32 vcc, 31, v200
	s_nop 1
	v_cndmask_b32_e32 v32, v185, v32, vcc
	v_cmp_lt_i32_e32 vcc, 32, v200
	s_nop 1
	v_cndmask_b32_e32 v33, v185, v33, vcc
	v_cmp_lt_i32_e32 vcc, 33, v200
	s_nop 1
	v_cndmask_b32_e32 v34, v185, v34, vcc
	v_cmp_lt_i32_e32 vcc, 34, v200
	s_nop 1
	v_cndmask_b32_e32 v35, v185, v35, vcc
	v_cmp_lt_i32_e32 vcc, 39, v200
	s_nop 1
	v_cndmask_b32_e32 v36, v185, v36, vcc
	v_cmp_lt_i32_e32 vcc, 40, v200
	s_nop 1
	v_cndmask_b32_e32 v37, v185, v37, vcc
	v_cmp_lt_i32_e32 vcc, 41, v200
	s_nop 1
	v_cndmask_b32_e32 v38, v185, v38, vcc
	v_cmp_lt_i32_e32 vcc, 42, v200
	s_nop 1
	v_cndmask_b32_e32 v39, v185, v39, vcc
	v_cmp_lt_i32_e32 vcc, 47, v200
	s_nop 1
	v_cndmask_b32_e32 v40, v185, v40, vcc
	v_cmp_lt_i32_e32 vcc, 48, v200
	s_nop 1
	v_cndmask_b32_e32 v41, v185, v41, vcc
	v_cmp_lt_i32_e32 vcc, 49, v200
	s_nop 1
	v_cndmask_b32_e32 v42, v185, v42, vcc
	v_cmp_lt_i32_e32 vcc, 50, v200
	s_nop 1
	v_cndmask_b32_e32 v43, v185, v43, vcc
	v_cmp_lt_i32_e32 vcc, 55, v200
	s_nop 1
	v_cndmask_b32_e32 v44, v185, v44, vcc
	v_cmp_lt_i32_e32 vcc, 56, v200
	s_nop 1
	v_cndmask_b32_e32 v45, v185, v45, vcc
	v_cmp_lt_i32_e32 vcc, 57, v200
	s_nop 1
	v_cndmask_b32_e32 v46, v185, v46, vcc
	v_cmp_lt_i32_e32 vcc, 58, v200
	s_nop 1
	v_cndmask_b32_e32 v47, v185, v47, vcc
	s_branch .LBB0_830
